# attention tile loop: per-tile rendezvous (vmcnt0/lgkmcnt0/barrier) moved from the loop head into the PV segment after the last V fragment read; one rendezvous kept in front of the loop per unit; on to
# baseline (speedup 1.0000x reference)
.LBB0_1116:
	v_mov_b32_e32 v2, v0
	v_mov_b32_e32 v3, v0
	v_mov_b32_e32 v1, v0
	v_mov_b64_e32 v[22:23], v[2:3]
	v_mov_b64_e32 v[26:27], v[2:3]
	v_mov_b64_e32 v[30:31], v[2:3]
	v_mov_b64_e32 v[34:35], v[2:3]
	v_mov_b64_e32 v[38:39], v[2:3]
	v_mov_b64_e32 v[42:43], v[2:3]
	v_mov_b64_e32 v[46:47], v[2:3]
	v_mov_b64_e32 v[50:51], v[2:3]
	v_mov_b64_e32 v[54:55], v[2:3]
	v_mov_b64_e32 v[58:59], v[2:3]
	v_mov_b64_e32 v[62:63], v[2:3]
	v_mov_b64_e32 v[66:67], v[2:3]
	v_mov_b64_e32 v[70:71], v[2:3]
	v_mov_b64_e32 v[74:75], v[2:3]
	v_mov_b64_e32 v[78:79], v[2:3]
	v_mov_b64_e32 v[82:83], v[2:3]
	s_mov_b32 s91, s93
	s_mov_b32 s90, s92
	s_sub_i32 s50, 63, s87
	v_mov_b32_e32 v143, 0xf149f2ca
	v_mov_b64_e32 v[146:147], v[140:141]
	v_mov_b64_e32 v[148:149], v[138:139]
	v_mov_b64_e32 v[20:21], v[0:1]
	v_mov_b64_e32 v[24:25], v[0:1]
	v_mov_b64_e32 v[28:29], v[0:1]
	v_mov_b64_e32 v[32:33], v[0:1]
	v_mov_b64_e32 v[36:37], v[0:1]
	v_mov_b64_e32 v[40:41], v[0:1]
	v_mov_b64_e32 v[44:45], v[0:1]
	v_mov_b64_e32 v[48:49], v[0:1]
	v_mov_b64_e32 v[52:53], v[0:1]
	v_mov_b64_e32 v[56:57], v[0:1]
	v_mov_b64_e32 v[60:61], v[0:1]
	v_mov_b64_e32 v[64:65], v[0:1]
	v_mov_b64_e32 v[68:69], v[0:1]
	v_mov_b64_e32 v[72:73], v[0:1]
	v_mov_b64_e32 v[76:77], v[0:1]
	v_mov_b64_e32 v[80:81], v[0:1]
	v_mov_b32_e32 v1, 0
	s_mov_b32 s70, 0
	s_waitcnt vmcnt(0)
	s_waitcnt vmcnt(0)
	s_waitcnt lgkmcnt(0)
	s_barrier
.LBB0_1117:
	s_and_b32 s92, s70, 1
	s_add_i32 s70, s70, 1
	s_lshl_b32 s71, s92, 15
	v_add_u32_e32 v2, s71, v160
	v_add_u32_e32 v3, v2, v153
	v_add_u32_e32 v124, v2, v154
	v_add_u32_e32 v125, v2, v155
	v_add_u32_e32 v2, v2, v156
	ds_read_b128 v[84:87], v3
	ds_read_b128 v[88:91], v3 offset:2048
	ds_read_b128 v[92:95], v124
	ds_read_b128 v[96:99], v124 offset:2048
	ds_read_b128 v[100:103], v125
	ds_read_b128 v[104:107], v125 offset:2048
	ds_read_b128 v[108:111], v2
	ds_read_b128 v[112:115], v2 offset:2048
	ds_read_b128 v[116:119], v3 offset:16384
	ds_read_b128 v[166:169], v3 offset:18432
	ds_read_b128 v[120:123], v124 offset:16384
	ds_read_b128 v[170:173], v124 offset:18432
	ds_read_b128 v[174:177], v125 offset:16384
	ds_read_b128 v[178:181], v125 offset:18432
	ds_read_b128 v[182:185], v2 offset:16384
	ds_read_b128 v[186:189], v2 offset:18432
	s_cmp_lt_i32 s70, s69
	s_cbranch_scc0 .Latt_k_done
	s_xor_b32 s0, s71, 0x8000
	v_lshl_add_u64 v[128:129], s[52:53], 0, v[146:147]
	s_add_i32 s1, s79, s0
	v_lshl_add_u64 v[130:131], v[128:129], 0, s[20:21]
	s_mov_b32 m0, s1
	s_nop 0
	global_load_lds_dwordx4 v[130:131], off
	v_lshl_add_u64 v[130:131], v[128:129], 0, s[54:55]
	s_add_i32 m0, s1, 0x800
	s_nop 0
	global_load_lds_dwordx4 v[130:131], off
	v_lshl_add_u64 v[130:131], v[128:129], 0, s[56:57]
	s_add_i32 m0, s1, 0x4000
	v_lshl_add_u64 v[128:129], v[128:129], 0, s[58:59]
	global_load_lds_dwordx4 v[130:131], off
	s_add_i32 m0, s1, 0x4800
	s_nop 0
	global_load_lds_dwordx4 v[128:129], off

.LBB0_1126:
	v_sub_f32_e32 v128, v128, v143
	v_exp_f32_e32 v128, v128
	v_sub_f32_e32 v129, v129, v143
	v_exp_f32_e32 v129, v129
	v_sub_f32_e32 v130, v130, v143
	v_exp_f32_e32 v130, v130
	v_sub_f32_e32 v131, v131, v143
	v_exp_f32_e32 v131, v131
	v_sub_f32_e32 v124, v124, v143
	v_add_f32_e32 v165, 0, v128
	v_exp_f32_e32 v124, v124
	v_sub_f32_e32 v125, v125, v143
	v_add_f32_e32 v165, v129, v165
	v_exp_f32_e32 v125, v125
	v_sub_f32_e32 v126, v126, v143
	v_add_f32_e32 v165, v130, v165
	v_exp_f32_e32 v126, v126
	v_sub_f32_e32 v127, v127, v143
	v_add_f32_e32 v165, v131, v165
	v_exp_f32_e32 v127, v127
	v_sub_f32_e32 v120, v120, v143
	v_add_f32_e32 v165, v124, v165
	v_exp_f32_e32 v166, v120
	v_sub_f32_e32 v120, v121, v143
	v_add_f32_e32 v165, v125, v165
	v_exp_f32_e32 v167, v120
	v_sub_f32_e32 v120, v122, v143
	v_add_f32_e32 v165, v126, v165
	v_exp_f32_e32 v168, v120
	v_sub_f32_e32 v120, v123, v143
	v_add_f32_e32 v165, v127, v165
	v_exp_f32_e32 v123, v120
	v_sub_f32_e32 v116, v116, v143
	v_add_f32_e32 v120, v166, v165
	v_exp_f32_e32 v165, v116
	v_sub_f32_e32 v116, v117, v143
	v_add_f32_e32 v120, v167, v120
	v_exp_f32_e32 v117, v116
	v_sub_f32_e32 v116, v118, v143
	v_add_f32_e32 v120, v168, v120
	v_exp_f32_e32 v169, v116
	v_sub_f32_e32 v116, v119, v143
	v_add_f32_e32 v120, v123, v120
	v_exp_f32_e32 v170, v116
	v_add_f32_e32 v116, v165, v120
	v_add_f32_e32 v116, v117, v116
	v_add_f32_e32 v116, v169, v116
	v_add_f32_e32 v116, v170, v116
	v_fmac_f32_e32 v116, v1, v2
	v_cvt_pk_bf16_f32 v118, v128, v129
	v_cvt_pk_bf16_f32 v119, v130, v131
	v_cvt_pk_bf16_f32 v120, v124, v125
	v_cvt_pk_bf16_f32 v121, v126, v127
	v_cvt_pk_bf16_f32 v122, v166, v167
	v_cvt_pk_bf16_f32 v123, v168, v123
	v_cvt_pk_bf16_f32 v124, v165, v117
	v_cvt_pk_bf16_f32 v125, v169, v170
	s_waitcnt lgkmcnt(0)
	v_mfma_f32_16x16x32_bf16 v[80:83], v[100:103], v[118:121], v[80:83]
	v_mfma_f32_16x16x32_bf16 v[76:79], v[88:91], v[118:121], v[76:79]
	v_mfma_f32_16x16x32_bf16 v[72:75], v[92:95], v[118:121], v[72:75]
	v_mfma_f32_16x16x32_bf16 v[68:71], v[84:87], v[118:121], v[68:71]
	v_mfma_f32_16x16x32_bf16 v[80:83], v[112:115], v[122:125], v[80:83]
	v_mfma_f32_16x16x32_bf16 v[76:79], v[104:107], v[122:125], v[76:79]
	v_mfma_f32_16x16x32_bf16 v[72:75], v[108:111], v[122:125], v[72:75]
	v_mfma_f32_16x16x32_bf16 v[68:71], v[96:99], v[122:125], v[68:71]
	ds_read_b128 v[84:87], v3 offset:16384
	ds_read_b128 v[88:91], v3 offset:18432
	ds_read_b128 v[92:95], v145 offset:16384
	ds_read_b128 v[96:99], v145 offset:18432
	ds_read_b128 v[100:103], v3 offset:20480
	ds_read_b128 v[104:107], v3 offset:22528
	ds_read_b128 v[108:111], v145 offset:20480
	ds_read_b128 v[112:115], v145 offset:22528
	ds_read_b128 v[126:129], v3 offset:24576
	ds_read_b128 v[166:169], v3 offset:26624
	ds_read_b128 v[170:173], v145 offset:24576
	ds_read_b128 v[174:177], v145 offset:26624
	ds_read_b128 v[178:181], v3 offset:28672
	ds_read_b128 v[182:185], v3 offset:30720
	ds_read_b128 v[186:189], v145 offset:28672
	ds_read_b128 v[190:193], v145 offset:30720
	v_mfma_f32_16x16x32_bf16 v[64:67], v[194:197], v[118:121], v[64:67]
	v_mfma_f32_16x16x32_bf16 v[60:63], v[198:201], v[118:121], v[60:63]
	v_mfma_f32_16x16x32_bf16 v[56:59], v[210:213], v[118:121], v[56:59]
	v_mfma_f32_16x16x32_bf16 v[52:55], v[214:217], v[118:121], v[52:55]
	v_mfma_f32_16x16x32_bf16 v[64:67], v[202:205], v[122:125], v[64:67]
	v_mfma_f32_16x16x32_bf16 v[60:63], v[206:209], v[122:125], v[60:63]
	v_mfma_f32_16x16x32_bf16 v[56:59], v[218:221], v[122:125], v[56:59]
	v_mfma_f32_16x16x32_bf16 v[52:55], v[222:225], v[122:125], v[52:55]
	s_waitcnt vmcnt(0)
	s_waitcnt lgkmcnt(0)
	s_barrier
	v_mfma_f32_16x16x32_bf16 v[48:51], v[84:87], v[118:121], v[48:51]
	v_mfma_f32_16x16x32_bf16 v[44:47], v[88:91], v[118:121], v[44:47]
	v_mfma_f32_16x16x32_bf16 v[40:43], v[100:103], v[118:121], v[40:43]
	v_mfma_f32_16x16x32_bf16 v[36:39], v[104:107], v[118:121], v[36:39]
	v_mfma_f32_16x16x32_bf16 v[48:51], v[92:95], v[122:125], v[48:51]
	v_mfma_f32_16x16x32_bf16 v[44:47], v[96:99], v[122:125], v[44:47]
	v_mfma_f32_16x16x32_bf16 v[40:43], v[108:111], v[122:125], v[40:43]
	v_mfma_f32_16x16x32_bf16 v[36:39], v[112:115], v[122:125], v[36:39]
	s_waitcnt lgkmcnt(0)
	v_mfma_f32_16x16x32_bf16 v[32:35], v[126:129], v[118:121], v[32:35]
	v_mfma_f32_16x16x32_bf16 v[28:31], v[166:169], v[118:121], v[28:31]
	v_mfma_f32_16x16x32_bf16 v[24:27], v[178:181], v[118:121], v[24:27]
	v_mfma_f32_16x16x32_bf16 v[20:23], v[182:185], v[118:121], v[20:23]
	v_mfma_f32_16x16x32_bf16 v[32:35], v[170:173], v[122:125], v[32:35]
	v_mfma_f32_16x16x32_bf16 v[28:31], v[174:177], v[122:125], v[28:31]
	v_mfma_f32_16x16x32_bf16 v[24:27], v[186:189], v[122:125], v[24:27]
	v_mfma_f32_16x16x32_bf16 v[20:23], v[190:193], v[122:125], v[20:23]
	s_add_i32 s50, s50, 64
	v_lshl_add_u64 v[148:149], v[148:149], 0, s[60:61]
	s_cmp_eq_u32 s69, s70
	v_lshl_add_u64 v[146:147], v[146:147], 0, s[20:21]
	s_cbranch_scc1 .LBB0_1129
	v_mov_b32_e32 v1, v116
	s_branch .LBB0_1117
